# conformer conv FIR with v_pk_fma_f32: the even-tap and odd-tap accumulation chains of a token are the two halves of one packed f32 FMA (same order per chain); input rows converted in place
# speedup vs baseline: 1.0047x; 1.0047x over previous
.LBB0_440:
	ds_read_u16 v128, v99
	ds_read_u16 v129, v99 offset:1024
	ds_read_u16 v130, v99 offset:2048
	ds_read_u16 v131, v99 offset:3072
	ds_read_u16 v132, v99 offset:4096
	ds_read_u16 v133, v99 offset:5120
	ds_read_u16 v134, v99 offset:6144
	ds_read_u16 v135, v99 offset:7168
	ds_read_u16 v136, v99 offset:8192
	ds_read_u16 v137, v99 offset:9216
	ds_read_u16 v138, v99 offset:10240
	ds_read_u16 v139, v99 offset:11264
	ds_read_u16 v140, v99 offset:12288
	ds_read_u16 v141, v99 offset:13312
	s_waitcnt lgkmcnt(7)
	v_lshlrev_b32_e32 v128, 16, v128
	v_lshlrev_b32_e32 v129, 16, v129
	v_lshlrev_b32_e32 v130, 16, v130
	v_lshlrev_b32_e32 v131, 16, v131
	v_lshlrev_b32_e32 v132, 16, v132
	v_lshlrev_b32_e32 v133, 16, v133
	v_lshlrev_b32_e32 v134, 16, v134
	ds_read_u16 v142, v99 offset:14336
	ds_read_u16 v143, v99 offset:15360
	ds_read_u16 v144, v99 offset:16384
	ds_read_u16 v145, v99 offset:17408
	ds_read_u16 v146, v99 offset:18432
	ds_read_u16 v147, v99 offset:19456
	ds_read_u16 v148, v99 offset:20480
	s_waitcnt lgkmcnt(7)
	v_lshlrev_b32_e32 v135, 16, v135
	v_lshlrev_b32_e32 v136, 16, v136
	v_lshlrev_b32_e32 v137, 16, v137
	v_lshlrev_b32_e32 v138, 16, v138
	v_lshlrev_b32_e32 v139, 16, v139
	v_lshlrev_b32_e32 v140, 16, v140
	v_lshlrev_b32_e32 v141, 16, v141
	ds_read_u16 v149, v99 offset:21504
	ds_read_u16 v150, v99 offset:22528
	ds_read_u16 v151, v99 offset:23552
	ds_read_u16 v152, v99 offset:24576
	ds_read_u16 v153, v99 offset:25600
	ds_read_u16 v154, v99 offset:26624
	ds_read_u16 v155, v99 offset:27648
	s_waitcnt lgkmcnt(7)
	v_lshlrev_b32_e32 v142, 16, v142
	v_lshlrev_b32_e32 v143, 16, v143
	v_lshlrev_b32_e32 v144, 16, v144
	v_lshlrev_b32_e32 v145, 16, v145
	v_lshlrev_b32_e32 v146, 16, v146
	v_lshlrev_b32_e32 v147, 16, v147
	v_lshlrev_b32_e32 v148, 16, v148
	ds_read_u16 v156, v99 offset:28672
	ds_read_u16 v157, v99 offset:29696
	ds_read_u16 v158, v99 offset:30720
	ds_read_u16 v159, v99 offset:31744
	ds_read_u16 v160, v99 offset:32768
	ds_read_u16 v161, v99 offset:33792
	ds_read_u16 v162, v99 offset:34816
	s_waitcnt lgkmcnt(7)
	v_lshlrev_b32_e32 v149, 16, v149
	v_lshlrev_b32_e32 v150, 16, v150
	v_lshlrev_b32_e32 v151, 16, v151
	v_lshlrev_b32_e32 v152, 16, v152
	v_lshlrev_b32_e32 v153, 16, v153
	v_lshlrev_b32_e32 v154, 16, v154
	v_lshlrev_b32_e32 v155, 16, v155
	ds_read_u16 v163, v99 offset:35840
	ds_read_u16 v164, v99 offset:36864
	ds_read_u16 v165, v99 offset:37888
	ds_read_u16 v166, v99 offset:38912
	ds_read_u16 v167, v99 offset:39936
	ds_read_u16 v168, v99 offset:40960
	ds_read_u16 v169, v99 offset:41984
	s_waitcnt lgkmcnt(7)
	v_lshlrev_b32_e32 v156, 16, v156
	v_lshlrev_b32_e32 v157, 16, v157
	v_lshlrev_b32_e32 v158, 16, v158
	v_lshlrev_b32_e32 v159, 16, v159
	v_lshlrev_b32_e32 v160, 16, v160
	v_lshlrev_b32_e32 v161, 16, v161
	v_lshlrev_b32_e32 v162, 16, v162
	ds_read_u16 v170, v99 offset:43008
	ds_read_u16 v171, v99 offset:44032
	ds_read_u16 v174, v99 offset:45056
	ds_read_u16 v175, v99 offset:46080
	ds_read_u16 v176, v99 offset:47104
	ds_read_u16 v177, v99 offset:48128
	ds_read_u16 v178, v99 offset:49152
	s_waitcnt lgkmcnt(7)
	v_lshlrev_b32_e32 v163, 16, v163
	v_lshlrev_b32_e32 v164, 16, v164
	v_lshlrev_b32_e32 v165, 16, v165
	v_lshlrev_b32_e32 v166, 16, v166
	v_lshlrev_b32_e32 v167, 16, v167
	v_lshlrev_b32_e32 v168, 16, v168
	v_lshlrev_b32_e32 v169, 16, v169
	ds_read_u16 v179, v99 offset:50176
	ds_read_u16 v180, v99 offset:51200
	ds_read_u16 v181, v99 offset:52224
	ds_read_u16 v182, v99 offset:53248
	ds_read_u16 v183, v99 offset:54272
	ds_read_u16 v184, v99 offset:55296
	ds_read_u16 v185, v99 offset:56320
	s_waitcnt lgkmcnt(7)
	v_lshlrev_b32_e32 v170, 16, v170
	v_lshlrev_b32_e32 v171, 16, v171
	v_lshlrev_b32_e32 v174, 16, v174
	v_lshlrev_b32_e32 v175, 16, v175
	v_lshlrev_b32_e32 v176, 16, v176
	v_lshlrev_b32_e32 v177, 16, v177
	v_lshlrev_b32_e32 v178, 16, v178
	ds_read_u16 v186, v99 offset:57344
	ds_read_u16 v187, v99 offset:58368
	ds_read_u16 v188, v99 offset:59392
	ds_read_u16 v189, v99 offset:60416
	ds_read_u16 v190, v99 offset:61440
	ds_read_u16 v191, v99 offset:62464
	s_waitcnt lgkmcnt(6)
	v_lshlrev_b32_e32 v179, 16, v179
	v_lshlrev_b32_e32 v180, 16, v180
	v_lshlrev_b32_e32 v181, 16, v181
	v_lshlrev_b32_e32 v182, 16, v182
	v_lshlrev_b32_e32 v183, 16, v183
	v_lshlrev_b32_e32 v184, 16, v184
	v_lshlrev_b32_e32 v185, 16, v185
	s_waitcnt lgkmcnt(0)
	v_lshlrev_b32_e32 v186, 16, v186
	v_lshlrev_b32_e32 v187, 16, v187
	v_lshlrev_b32_e32 v188, 16, v188
	v_lshlrev_b32_e32 v189, 16, v189
	v_lshlrev_b32_e32 v190, 16, v190
	v_lshlrev_b32_e32 v191, 16, v191
	s_waitcnt vmcnt(4)
	v_mov_b32_e32 v200, v67
	v_mov_b32_e32 v201, v68
	v_mov_b32_e32 v202, v69
	v_mov_b32_e32 v203, v70
	v_mov_b32_e32 v204, v71
	v_mov_b32_e32 v205, v72
	v_mov_b32_e32 v206, v73
	v_mov_b32_e32 v207, v74
	v_mov_b32_e32 v208, v75
	v_mov_b32_e32 v209, v76
	v_mov_b32_e32 v210, v77
	v_mov_b32_e32 v211, v78
	v_mov_b32_e32 v212, v79
	v_mov_b32_e32 v213, v80
	v_mov_b32_e32 v214, v81
	v_mov_b32_e32 v215, v82
	v_mov_b32_e32 v216, v83
	v_mov_b32_e32 v217, v84
	v_mov_b32_e32 v218, v85
	v_mov_b32_e32 v219, v86
	v_mov_b32_e32 v220, v87
	v_mov_b32_e32 v221, v88
	v_mov_b32_e32 v222, v89
	v_mov_b32_e32 v223, v90
	v_mov_b32_e32 v224, v91
	v_mov_b32_e32 v225, v92
	v_mov_b32_e32 v226, v93
	v_mov_b32_e32 v227, v94
	v_mov_b32_e32 v228, v95
	v_mov_b32_e32 v229, v96
	v_mov_b32_e32 v230, v97
	v_mov_b32_e32 v231, 0
	v_pk_fma_f32 v[192:193], v[66:67], v[128:129], v[230:231]
	v_pk_fma_f32 v[192:193], v[68:69], v[130:131], v[192:193]
	v_pk_fma_f32 v[192:193], v[70:71], v[132:133], v[192:193]
	v_pk_fma_f32 v[192:193], v[72:73], v[134:135], v[192:193]
	v_pk_fma_f32 v[192:193], v[74:75], v[136:137], v[192:193]
	v_pk_fma_f32 v[192:193], v[76:77], v[138:139], v[192:193]
	v_pk_fma_f32 v[192:193], v[78:79], v[140:141], v[192:193]
	v_pk_fma_f32 v[192:193], v[80:81], v[142:143], v[192:193]
	v_pk_fma_f32 v[192:193], v[82:83], v[144:145], v[192:193]
	v_pk_fma_f32 v[192:193], v[84:85], v[146:147], v[192:193]
	v_pk_fma_f32 v[192:193], v[86:87], v[148:149], v[192:193]
	v_pk_fma_f32 v[192:193], v[88:89], v[150:151], v[192:193]
	v_pk_fma_f32 v[192:193], v[90:91], v[152:153], v[192:193]
	v_pk_fma_f32 v[192:193], v[92:93], v[154:155], v[192:193]
	v_pk_fma_f32 v[192:193], v[94:95], v[156:157], v[192:193]
	v_fmac_f32_e32 v192, v96, v158
	v_add_f32_e32 v232, v193, v192
	v_fma_f32 v195, v66, v129, v97
	v_mov_b32_e32 v194, 0
	v_pk_fma_f32 v[194:195], v[200:201], v[130:131], v[194:195]
	v_pk_fma_f32 v[194:195], v[202:203], v[132:133], v[194:195]
	v_pk_fma_f32 v[194:195], v[204:205], v[134:135], v[194:195]
	v_pk_fma_f32 v[194:195], v[206:207], v[136:137], v[194:195]
	v_pk_fma_f32 v[194:195], v[208:209], v[138:139], v[194:195]
	v_pk_fma_f32 v[194:195], v[210:211], v[140:141], v[194:195]
	v_pk_fma_f32 v[194:195], v[212:213], v[142:143], v[194:195]
	v_pk_fma_f32 v[194:195], v[214:215], v[144:145], v[194:195]
	v_pk_fma_f32 v[194:195], v[216:217], v[146:147], v[194:195]
	v_pk_fma_f32 v[194:195], v[218:219], v[148:149], v[194:195]
	v_pk_fma_f32 v[194:195], v[220:221], v[150:151], v[194:195]
	v_pk_fma_f32 v[194:195], v[222:223], v[152:153], v[194:195]
	v_pk_fma_f32 v[194:195], v[224:225], v[154:155], v[194:195]
	v_pk_fma_f32 v[194:195], v[226:227], v[156:157], v[194:195]
	v_pk_fma_f32 v[194:195], v[228:229], v[158:159], v[194:195]
	v_add_f32_e32 v233, v194, v195
	ds_write2st64_b32 v100, v232, v233 offset1:8
	v_pk_fma_f32 v[196:197], v[66:67], v[130:131], v[230:231]
	v_pk_fma_f32 v[196:197], v[68:69], v[132:133], v[196:197]
	v_pk_fma_f32 v[196:197], v[70:71], v[134:135], v[196:197]
	v_pk_fma_f32 v[196:197], v[72:73], v[136:137], v[196:197]
	v_pk_fma_f32 v[196:197], v[74:75], v[138:139], v[196:197]
	v_pk_fma_f32 v[196:197], v[76:77], v[140:141], v[196:197]
	v_pk_fma_f32 v[196:197], v[78:79], v[142:143], v[196:197]
	v_pk_fma_f32 v[196:197], v[80:81], v[144:145], v[196:197]
	v_pk_fma_f32 v[196:197], v[82:83], v[146:147], v[196:197]
	v_pk_fma_f32 v[196:197], v[84:85], v[148:149], v[196:197]
	v_pk_fma_f32 v[196:197], v[86:87], v[150:151], v[196:197]
	v_pk_fma_f32 v[196:197], v[88:89], v[152:153], v[196:197]
	v_pk_fma_f32 v[196:197], v[90:91], v[154:155], v[196:197]
	v_pk_fma_f32 v[196:197], v[92:93], v[156:157], v[196:197]
	v_pk_fma_f32 v[196:197], v[94:95], v[158:159], v[196:197]
	v_fmac_f32_e32 v196, v96, v160
	v_add_f32_e32 v234, v197, v196
	v_fma_f32 v199, v66, v131, v97
	v_mov_b32_e32 v198, 0
	v_pk_fma_f32 v[198:199], v[200:201], v[132:133], v[198:199]
	v_pk_fma_f32 v[198:199], v[202:203], v[134:135], v[198:199]
	v_pk_fma_f32 v[198:199], v[204:205], v[136:137], v[198:199]
	v_pk_fma_f32 v[198:199], v[206:207], v[138:139], v[198:199]
	v_pk_fma_f32 v[198:199], v[208:209], v[140:141], v[198:199]
	v_pk_fma_f32 v[198:199], v[210:211], v[142:143], v[198:199]
	v_pk_fma_f32 v[198:199], v[212:213], v[144:145], v[198:199]
	v_pk_fma_f32 v[198:199], v[214:215], v[146:147], v[198:199]
	v_pk_fma_f32 v[198:199], v[216:217], v[148:149], v[198:199]
	v_pk_fma_f32 v[198:199], v[218:219], v[150:151], v[198:199]
	v_pk_fma_f32 v[198:199], v[220:221], v[152:153], v[198:199]
	v_pk_fma_f32 v[198:199], v[222:223], v[154:155], v[198:199]
	v_pk_fma_f32 v[198:199], v[224:225], v[156:157], v[198:199]
	v_pk_fma_f32 v[198:199], v[226:227], v[158:159], v[198:199]
	v_pk_fma_f32 v[198:199], v[228:229], v[160:161], v[198:199]
	v_add_f32_e32 v235, v198, v199
	ds_write2st64_b32 v100, v234, v235 offset0:16 offset1:24
	v_pk_fma_f32 v[192:193], v[66:67], v[132:133], v[230:231]
	v_pk_fma_f32 v[192:193], v[68:69], v[134:135], v[192:193]
	v_pk_fma_f32 v[192:193], v[70:71], v[136:137], v[192:193]
	v_pk_fma_f32 v[192:193], v[72:73], v[138:139], v[192:193]
	v_pk_fma_f32 v[192:193], v[74:75], v[140:141], v[192:193]
	v_pk_fma_f32 v[192:193], v[76:77], v[142:143], v[192:193]
	v_pk_fma_f32 v[192:193], v[78:79], v[144:145], v[192:193]
	v_pk_fma_f32 v[192:193], v[80:81], v[146:147], v[192:193]
	v_pk_fma_f32 v[192:193], v[82:83], v[148:149], v[192:193]
	v_pk_fma_f32 v[192:193], v[84:85], v[150:151], v[192:193]
	v_pk_fma_f32 v[192:193], v[86:87], v[152:153], v[192:193]
	v_pk_fma_f32 v[192:193], v[88:89], v[154:155], v[192:193]
	v_pk_fma_f32 v[192:193], v[90:91], v[156:157], v[192:193]
	v_pk_fma_f32 v[192:193], v[92:93], v[158:159], v[192:193]
	v_pk_fma_f32 v[192:193], v[94:95], v[160:161], v[192:193]
	v_fmac_f32_e32 v192, v96, v162
	v_add_f32_e32 v232, v193, v192
	v_fma_f32 v195, v66, v133, v97
	v_mov_b32_e32 v194, 0
	v_pk_fma_f32 v[194:195], v[200:201], v[134:135], v[194:195]
	v_pk_fma_f32 v[194:195], v[202:203], v[136:137], v[194:195]
	v_pk_fma_f32 v[194:195], v[204:205], v[138:139], v[194:195]
	v_pk_fma_f32 v[194:195], v[206:207], v[140:141], v[194:195]
	v_pk_fma_f32 v[194:195], v[208:209], v[142:143], v[194:195]
	v_pk_fma_f32 v[194:195], v[210:211], v[144:145], v[194:195]
	v_pk_fma_f32 v[194:195], v[212:213], v[146:147], v[194:195]
	v_pk_fma_f32 v[194:195], v[214:215], v[148:149], v[194:195]
	v_pk_fma_f32 v[194:195], v[216:217], v[150:151], v[194:195]
	v_pk_fma_f32 v[194:195], v[218:219], v[152:153], v[194:195]
	v_pk_fma_f32 v[194:195], v[220:221], v[154:155], v[194:195]
	v_pk_fma_f32 v[194:195], v[222:223], v[156:157], v[194:195]
	v_pk_fma_f32 v[194:195], v[224:225], v[158:159], v[194:195]
	v_pk_fma_f32 v[194:195], v[226:227], v[160:161], v[194:195]
	v_pk_fma_f32 v[194:195], v[228:229], v[162:163], v[194:195]
	v_add_f32_e32 v233, v194, v195
	ds_write2st64_b32 v100, v232, v233 offset0:32 offset1:40
	v_pk_fma_f32 v[196:197], v[66:67], v[134:135], v[230:231]
	v_pk_fma_f32 v[196:197], v[68:69], v[136:137], v[196:197]
	v_pk_fma_f32 v[196:197], v[70:71], v[138:139], v[196:197]
	v_pk_fma_f32 v[196:197], v[72:73], v[140:141], v[196:197]
	v_pk_fma_f32 v[196:197], v[74:75], v[142:143], v[196:197]
	v_pk_fma_f32 v[196:197], v[76:77], v[144:145], v[196:197]
	v_pk_fma_f32 v[196:197], v[78:79], v[146:147], v[196:197]
	v_pk_fma_f32 v[196:197], v[80:81], v[148:149], v[196:197]
	v_pk_fma_f32 v[196:197], v[82:83], v[150:151], v[196:197]
	v_pk_fma_f32 v[196:197], v[84:85], v[152:153], v[196:197]
	v_pk_fma_f32 v[196:197], v[86:87], v[154:155], v[196:197]
	v_pk_fma_f32 v[196:197], v[88:89], v[156:157], v[196:197]
	v_pk_fma_f32 v[196:197], v[90:91], v[158:159], v[196:197]
	v_pk_fma_f32 v[196:197], v[92:93], v[160:161], v[196:197]
	v_pk_fma_f32 v[196:197], v[94:95], v[162:163], v[196:197]
	v_fmac_f32_e32 v196, v96, v164
	v_add_f32_e32 v234, v197, v196
	v_fma_f32 v199, v66, v135, v97
	v_mov_b32_e32 v198, 0
	v_pk_fma_f32 v[198:199], v[200:201], v[136:137], v[198:199]
	v_pk_fma_f32 v[198:199], v[202:203], v[138:139], v[198:199]
	v_pk_fma_f32 v[198:199], v[204:205], v[140:141], v[198:199]
	v_pk_fma_f32 v[198:199], v[206:207], v[142:143], v[198:199]
	v_pk_fma_f32 v[198:199], v[208:209], v[144:145], v[198:199]
	v_pk_fma_f32 v[198:199], v[210:211], v[146:147], v[198:199]
	v_pk_fma_f32 v[198:199], v[212:213], v[148:149], v[198:199]
	v_pk_fma_f32 v[198:199], v[214:215], v[150:151], v[198:199]
	v_pk_fma_f32 v[198:199], v[216:217], v[152:153], v[198:199]
	v_pk_fma_f32 v[198:199], v[218:219], v[154:155], v[198:199]
	v_pk_fma_f32 v[198:199], v[220:221], v[156:157], v[198:199]
	v_pk_fma_f32 v[198:199], v[222:223], v[158:159], v[198:199]
	v_pk_fma_f32 v[198:199], v[224:225], v[160:161], v[198:199]
	v_pk_fma_f32 v[198:199], v[226:227], v[162:163], v[198:199]
	v_pk_fma_f32 v[198:199], v[228:229], v[164:165], v[198:199]
	v_add_f32_e32 v235, v198, v199
	ds_write2st64_b32 v100, v234, v235 offset0:48 offset1:56
	v_pk_fma_f32 v[192:193], v[66:67], v[136:137], v[230:231]
	v_pk_fma_f32 v[192:193], v[68:69], v[138:139], v[192:193]
	v_pk_fma_f32 v[192:193], v[70:71], v[140:141], v[192:193]
	v_pk_fma_f32 v[192:193], v[72:73], v[142:143], v[192:193]
	v_pk_fma_f32 v[192:193], v[74:75], v[144:145], v[192:193]
	v_pk_fma_f32 v[192:193], v[76:77], v[146:147], v[192:193]
	v_pk_fma_f32 v[192:193], v[78:79], v[148:149], v[192:193]
	v_pk_fma_f32 v[192:193], v[80:81], v[150:151], v[192:193]
	v_pk_fma_f32 v[192:193], v[82:83], v[152:153], v[192:193]
	v_pk_fma_f32 v[192:193], v[84:85], v[154:155], v[192:193]
	v_pk_fma_f32 v[192:193], v[86:87], v[156:157], v[192:193]
	v_pk_fma_f32 v[192:193], v[88:89], v[158:159], v[192:193]
	v_pk_fma_f32 v[192:193], v[90:91], v[160:161], v[192:193]
	v_pk_fma_f32 v[192:193], v[92:93], v[162:163], v[192:193]
	v_pk_fma_f32 v[192:193], v[94:95], v[164:165], v[192:193]
	v_fmac_f32_e32 v192, v96, v166
	v_add_f32_e32 v232, v193, v192
	v_fma_f32 v195, v66, v137, v97
	v_mov_b32_e32 v194, 0
	v_pk_fma_f32 v[194:195], v[200:201], v[138:139], v[194:195]
	v_pk_fma_f32 v[194:195], v[202:203], v[140:141], v[194:195]
	v_pk_fma_f32 v[194:195], v[204:205], v[142:143], v[194:195]
	v_pk_fma_f32 v[194:195], v[206:207], v[144:145], v[194:195]
	v_pk_fma_f32 v[194:195], v[208:209], v[146:147], v[194:195]
	v_pk_fma_f32 v[194:195], v[210:211], v[148:149], v[194:195]
	v_pk_fma_f32 v[194:195], v[212:213], v[150:151], v[194:195]
	v_pk_fma_f32 v[194:195], v[214:215], v[152:153], v[194:195]
	v_pk_fma_f32 v[194:195], v[216:217], v[154:155], v[194:195]
	v_pk_fma_f32 v[194:195], v[218:219], v[156:157], v[194:195]
	v_pk_fma_f32 v[194:195], v[220:221], v[158:159], v[194:195]
	v_pk_fma_f32 v[194:195], v[222:223], v[160:161], v[194:195]
	v_pk_fma_f32 v[194:195], v[224:225], v[162:163], v[194:195]
	v_pk_fma_f32 v[194:195], v[226:227], v[164:165], v[194:195]
	v_pk_fma_f32 v[194:195], v[228:229], v[166:167], v[194:195]
	v_add_f32_e32 v233, v194, v195
	ds_write2st64_b32 v100, v232, v233 offset0:64 offset1:72
	v_pk_fma_f32 v[196:197], v[66:67], v[138:139], v[230:231]
	v_pk_fma_f32 v[196:197], v[68:69], v[140:141], v[196:197]
	v_pk_fma_f32 v[196:197], v[70:71], v[142:143], v[196:197]
	v_pk_fma_f32 v[196:197], v[72:73], v[144:145], v[196:197]
	v_pk_fma_f32 v[196:197], v[74:75], v[146:147], v[196:197]
	v_pk_fma_f32 v[196:197], v[76:77], v[148:149], v[196:197]
	v_pk_fma_f32 v[196:197], v[78:79], v[150:151], v[196:197]
	v_pk_fma_f32 v[196:197], v[80:81], v[152:153], v[196:197]
	v_pk_fma_f32 v[196:197], v[82:83], v[154:155], v[196:197]
	v_pk_fma_f32 v[196:197], v[84:85], v[156:157], v[196:197]
	v_pk_fma_f32 v[196:197], v[86:87], v[158:159], v[196:197]
	v_pk_fma_f32 v[196:197], v[88:89], v[160:161], v[196:197]
	v_pk_fma_f32 v[196:197], v[90:91], v[162:163], v[196:197]
	v_pk_fma_f32 v[196:197], v[92:93], v[164:165], v[196:197]
	v_pk_fma_f32 v[196:197], v[94:95], v[166:167], v[196:197]
	v_fmac_f32_e32 v196, v96, v168
	v_add_f32_e32 v234, v197, v196
	v_fma_f32 v199, v66, v139, v97
	v_mov_b32_e32 v198, 0
	v_pk_fma_f32 v[198:199], v[200:201], v[140:141], v[198:199]
	v_pk_fma_f32 v[198:199], v[202:203], v[142:143], v[198:199]
	v_pk_fma_f32 v[198:199], v[204:205], v[144:145], v[198:199]
	v_pk_fma_f32 v[198:199], v[206:207], v[146:147], v[198:199]
	v_pk_fma_f32 v[198:199], v[208:209], v[148:149], v[198:199]
	v_pk_fma_f32 v[198:199], v[210:211], v[150:151], v[198:199]
	v_pk_fma_f32 v[198:199], v[212:213], v[152:153], v[198:199]
	v_pk_fma_f32 v[198:199], v[214:215], v[154:155], v[198:199]
	v_pk_fma_f32 v[198:199], v[216:217], v[156:157], v[198:199]
	v_pk_fma_f32 v[198:199], v[218:219], v[158:159], v[198:199]
	v_pk_fma_f32 v[198:199], v[220:221], v[160:161], v[198:199]
	v_pk_fma_f32 v[198:199], v[222:223], v[162:163], v[198:199]
	v_pk_fma_f32 v[198:199], v[224:225], v[164:165], v[198:199]
	v_pk_fma_f32 v[198:199], v[226:227], v[166:167], v[198:199]
	v_pk_fma_f32 v[198:199], v[228:229], v[168:169], v[198:199]
	v_add_f32_e32 v235, v198, v199
	ds_write2st64_b32 v100, v234, v235 offset0:80 offset1:88
	v_pk_fma_f32 v[192:193], v[66:67], v[140:141], v[230:231]
	v_pk_fma_f32 v[192:193], v[68:69], v[142:143], v[192:193]
	v_pk_fma_f32 v[192:193], v[70:71], v[144:145], v[192:193]
	v_pk_fma_f32 v[192:193], v[72:73], v[146:147], v[192:193]
	v_pk_fma_f32 v[192:193], v[74:75], v[148:149], v[192:193]
	v_pk_fma_f32 v[192:193], v[76:77], v[150:151], v[192:193]
	v_pk_fma_f32 v[192:193], v[78:79], v[152:153], v[192:193]
	v_pk_fma_f32 v[192:193], v[80:81], v[154:155], v[192:193]
	v_pk_fma_f32 v[192:193], v[82:83], v[156:157], v[192:193]
	v_pk_fma_f32 v[192:193], v[84:85], v[158:159], v[192:193]
	v_pk_fma_f32 v[192:193], v[86:87], v[160:161], v[192:193]
	v_pk_fma_f32 v[192:193], v[88:89], v[162:163], v[192:193]
	v_pk_fma_f32 v[192:193], v[90:91], v[164:165], v[192:193]
	v_pk_fma_f32 v[192:193], v[92:93], v[166:167], v[192:193]
	v_pk_fma_f32 v[192:193], v[94:95], v[168:169], v[192:193]
	v_fmac_f32_e32 v192, v96, v170
	v_add_f32_e32 v232, v193, v192
	v_fma_f32 v195, v66, v141, v97
	v_mov_b32_e32 v194, 0
	v_pk_fma_f32 v[194:195], v[200:201], v[142:143], v[194:195]
	v_pk_fma_f32 v[194:195], v[202:203], v[144:145], v[194:195]
	v_pk_fma_f32 v[194:195], v[204:205], v[146:147], v[194:195]
	v_pk_fma_f32 v[194:195], v[206:207], v[148:149], v[194:195]
	v_pk_fma_f32 v[194:195], v[208:209], v[150:151], v[194:195]
	v_pk_fma_f32 v[194:195], v[210:211], v[152:153], v[194:195]
	v_pk_fma_f32 v[194:195], v[212:213], v[154:155], v[194:195]
	v_pk_fma_f32 v[194:195], v[214:215], v[156:157], v[194:195]
	v_pk_fma_f32 v[194:195], v[216:217], v[158:159], v[194:195]
	v_pk_fma_f32 v[194:195], v[218:219], v[160:161], v[194:195]
	v_pk_fma_f32 v[194:195], v[220:221], v[162:163], v[194:195]
	v_pk_fma_f32 v[194:195], v[222:223], v[164:165], v[194:195]
	v_pk_fma_f32 v[194:195], v[224:225], v[166:167], v[194:195]
	v_pk_fma_f32 v[194:195], v[226:227], v[168:169], v[194:195]
	v_pk_fma_f32 v[194:195], v[228:229], v[170:171], v[194:195]
	v_add_f32_e32 v233, v194, v195
	ds_write2st64_b32 v100, v232, v233 offset0:96 offset1:104
	v_pk_fma_f32 v[196:197], v[66:67], v[142:143], v[230:231]
	v_pk_fma_f32 v[196:197], v[68:69], v[144:145], v[196:197]
	v_pk_fma_f32 v[196:197], v[70:71], v[146:147], v[196:197]
	v_pk_fma_f32 v[196:197], v[72:73], v[148:149], v[196:197]
	v_pk_fma_f32 v[196:197], v[74:75], v[150:151], v[196:197]
	v_pk_fma_f32 v[196:197], v[76:77], v[152:153], v[196:197]
	v_pk_fma_f32 v[196:197], v[78:79], v[154:155], v[196:197]
	v_pk_fma_f32 v[196:197], v[80:81], v[156:157], v[196:197]
	v_pk_fma_f32 v[196:197], v[82:83], v[158:159], v[196:197]
	v_pk_fma_f32 v[196:197], v[84:85], v[160:161], v[196:197]
	v_pk_fma_f32 v[196:197], v[86:87], v[162:163], v[196:197]
	v_pk_fma_f32 v[196:197], v[88:89], v[164:165], v[196:197]
	v_pk_fma_f32 v[196:197], v[90:91], v[166:167], v[196:197]
	v_pk_fma_f32 v[196:197], v[92:93], v[168:169], v[196:197]
	v_pk_fma_f32 v[196:197], v[94:95], v[170:171], v[196:197]
	v_fmac_f32_e32 v196, v96, v174
	v_add_f32_e32 v234, v197, v196
	v_fma_f32 v199, v66, v143, v97
	v_mov_b32_e32 v198, 0
	v_pk_fma_f32 v[198:199], v[200:201], v[144:145], v[198:199]
	v_pk_fma_f32 v[198:199], v[202:203], v[146:147], v[198:199]
	v_pk_fma_f32 v[198:199], v[204:205], v[148:149], v[198:199]
	v_pk_fma_f32 v[198:199], v[206:207], v[150:151], v[198:199]
	v_pk_fma_f32 v[198:199], v[208:209], v[152:153], v[198:199]
	v_pk_fma_f32 v[198:199], v[210:211], v[154:155], v[198:199]
	v_pk_fma_f32 v[198:199], v[212:213], v[156:157], v[198:199]
	v_pk_fma_f32 v[198:199], v[214:215], v[158:159], v[198:199]
	v_pk_fma_f32 v[198:199], v[216:217], v[160:161], v[198:199]
	v_pk_fma_f32 v[198:199], v[218:219], v[162:163], v[198:199]
	v_pk_fma_f32 v[198:199], v[220:221], v[164:165], v[198:199]
	v_pk_fma_f32 v[198:199], v[222:223], v[166:167], v[198:199]
	v_pk_fma_f32 v[198:199], v[224:225], v[168:169], v[198:199]
	v_pk_fma_f32 v[198:199], v[226:227], v[170:171], v[198:199]
	v_pk_fma_f32 v[198:199], v[228:229], v[174:175], v[198:199]
	v_add_f32_e32 v235, v198, v199
	ds_write2st64_b32 v100, v234, v235 offset0:112 offset1:120
	v_pk_fma_f32 v[192:193], v[66:67], v[144:145], v[230:231]
	v_pk_fma_f32 v[192:193], v[68:69], v[146:147], v[192:193]
	v_pk_fma_f32 v[192:193], v[70:71], v[148:149], v[192:193]
	v_pk_fma_f32 v[192:193], v[72:73], v[150:151], v[192:193]
	v_pk_fma_f32 v[192:193], v[74:75], v[152:153], v[192:193]
	v_pk_fma_f32 v[192:193], v[76:77], v[154:155], v[192:193]
	v_pk_fma_f32 v[192:193], v[78:79], v[156:157], v[192:193]
	v_pk_fma_f32 v[192:193], v[80:81], v[158:159], v[192:193]
	v_pk_fma_f32 v[192:193], v[82:83], v[160:161], v[192:193]
	v_pk_fma_f32 v[192:193], v[84:85], v[162:163], v[192:193]
	v_pk_fma_f32 v[192:193], v[86:87], v[164:165], v[192:193]
	v_pk_fma_f32 v[192:193], v[88:89], v[166:167], v[192:193]
	v_pk_fma_f32 v[192:193], v[90:91], v[168:169], v[192:193]
	v_pk_fma_f32 v[192:193], v[92:93], v[170:171], v[192:193]
	v_pk_fma_f32 v[192:193], v[94:95], v[174:175], v[192:193]
	v_fmac_f32_e32 v192, v96, v176
	v_add_f32_e32 v232, v193, v192
	v_fma_f32 v195, v66, v145, v97
	v_mov_b32_e32 v194, 0
	v_pk_fma_f32 v[194:195], v[200:201], v[146:147], v[194:195]
	v_pk_fma_f32 v[194:195], v[202:203], v[148:149], v[194:195]
	v_pk_fma_f32 v[194:195], v[204:205], v[150:151], v[194:195]
	v_pk_fma_f32 v[194:195], v[206:207], v[152:153], v[194:195]
	v_pk_fma_f32 v[194:195], v[208:209], v[154:155], v[194:195]
	v_pk_fma_f32 v[194:195], v[210:211], v[156:157], v[194:195]
	v_pk_fma_f32 v[194:195], v[212:213], v[158:159], v[194:195]
	v_pk_fma_f32 v[194:195], v[214:215], v[160:161], v[194:195]
	v_pk_fma_f32 v[194:195], v[216:217], v[162:163], v[194:195]
	v_pk_fma_f32 v[194:195], v[218:219], v[164:165], v[194:195]
	v_pk_fma_f32 v[194:195], v[220:221], v[166:167], v[194:195]
	v_pk_fma_f32 v[194:195], v[222:223], v[168:169], v[194:195]
	v_pk_fma_f32 v[194:195], v[224:225], v[170:171], v[194:195]
	v_pk_fma_f32 v[194:195], v[226:227], v[174:175], v[194:195]
	v_pk_fma_f32 v[194:195], v[228:229], v[176:177], v[194:195]
	v_add_f32_e32 v233, v194, v195
	ds_write2st64_b32 v100, v232, v233 offset0:128 offset1:136
	v_pk_fma_f32 v[196:197], v[66:67], v[146:147], v[230:231]
	v_pk_fma_f32 v[196:197], v[68:69], v[148:149], v[196:197]
	v_pk_fma_f32 v[196:197], v[70:71], v[150:151], v[196:197]
	v_pk_fma_f32 v[196:197], v[72:73], v[152:153], v[196:197]
	v_pk_fma_f32 v[196:197], v[74:75], v[154:155], v[196:197]
	v_pk_fma_f32 v[196:197], v[76:77], v[156:157], v[196:197]
	v_pk_fma_f32 v[196:197], v[78:79], v[158:159], v[196:197]
	v_pk_fma_f32 v[196:197], v[80:81], v[160:161], v[196:197]
	v_pk_fma_f32 v[196:197], v[82:83], v[162:163], v[196:197]
	v_pk_fma_f32 v[196:197], v[84:85], v[164:165], v[196:197]
	v_pk_fma_f32 v[196:197], v[86:87], v[166:167], v[196:197]
	v_pk_fma_f32 v[196:197], v[88:89], v[168:169], v[196:197]
	v_pk_fma_f32 v[196:197], v[90:91], v[170:171], v[196:197]
	v_pk_fma_f32 v[196:197], v[92:93], v[174:175], v[196:197]
	v_pk_fma_f32 v[196:197], v[94:95], v[176:177], v[196:197]
	v_fmac_f32_e32 v196, v96, v178
	v_add_f32_e32 v234, v197, v196
	v_fma_f32 v199, v66, v147, v97
	v_mov_b32_e32 v198, 0
	v_pk_fma_f32 v[198:199], v[200:201], v[148:149], v[198:199]
	v_pk_fma_f32 v[198:199], v[202:203], v[150:151], v[198:199]
	v_pk_fma_f32 v[198:199], v[204:205], v[152:153], v[198:199]
	v_pk_fma_f32 v[198:199], v[206:207], v[154:155], v[198:199]
	v_pk_fma_f32 v[198:199], v[208:209], v[156:157], v[198:199]
	v_pk_fma_f32 v[198:199], v[210:211], v[158:159], v[198:199]
	v_pk_fma_f32 v[198:199], v[212:213], v[160:161], v[198:199]
	v_pk_fma_f32 v[198:199], v[214:215], v[162:163], v[198:199]
	v_pk_fma_f32 v[198:199], v[216:217], v[164:165], v[198:199]
	v_pk_fma_f32 v[198:199], v[218:219], v[166:167], v[198:199]
	v_pk_fma_f32 v[198:199], v[220:221], v[168:169], v[198:199]
	v_pk_fma_f32 v[198:199], v[222:223], v[170:171], v[198:199]
	v_pk_fma_f32 v[198:199], v[224:225], v[174:175], v[198:199]
	v_pk_fma_f32 v[198:199], v[226:227], v[176:177], v[198:199]
	v_pk_fma_f32 v[198:199], v[228:229], v[178:179], v[198:199]
	v_add_f32_e32 v235, v198, v199
	ds_write2st64_b32 v100, v234, v235 offset0:144 offset1:152
	v_pk_fma_f32 v[192:193], v[66:67], v[148:149], v[230:231]
	v_pk_fma_f32 v[192:193], v[68:69], v[150:151], v[192:193]
	v_pk_fma_f32 v[192:193], v[70:71], v[152:153], v[192:193]
	v_pk_fma_f32 v[192:193], v[72:73], v[154:155], v[192:193]
	v_pk_fma_f32 v[192:193], v[74:75], v[156:157], v[192:193]
	v_pk_fma_f32 v[192:193], v[76:77], v[158:159], v[192:193]
	v_pk_fma_f32 v[192:193], v[78:79], v[160:161], v[192:193]
	v_pk_fma_f32 v[192:193], v[80:81], v[162:163], v[192:193]
	v_pk_fma_f32 v[192:193], v[82:83], v[164:165], v[192:193]
	v_pk_fma_f32 v[192:193], v[84:85], v[166:167], v[192:193]
	v_pk_fma_f32 v[192:193], v[86:87], v[168:169], v[192:193]
	v_pk_fma_f32 v[192:193], v[88:89], v[170:171], v[192:193]
	v_pk_fma_f32 v[192:193], v[90:91], v[174:175], v[192:193]
	v_pk_fma_f32 v[192:193], v[92:93], v[176:177], v[192:193]
	v_pk_fma_f32 v[192:193], v[94:95], v[178:179], v[192:193]
	v_fmac_f32_e32 v192, v96, v180
	v_add_f32_e32 v232, v193, v192
	v_fma_f32 v195, v66, v149, v97
	v_mov_b32_e32 v194, 0
	v_pk_fma_f32 v[194:195], v[200:201], v[150:151], v[194:195]
	v_pk_fma_f32 v[194:195], v[202:203], v[152:153], v[194:195]
	v_pk_fma_f32 v[194:195], v[204:205], v[154:155], v[194:195]
	v_pk_fma_f32 v[194:195], v[206:207], v[156:157], v[194:195]
	v_pk_fma_f32 v[194:195], v[208:209], v[158:159], v[194:195]
	v_pk_fma_f32 v[194:195], v[210:211], v[160:161], v[194:195]
	v_pk_fma_f32 v[194:195], v[212:213], v[162:163], v[194:195]
	v_pk_fma_f32 v[194:195], v[214:215], v[164:165], v[194:195]
	v_pk_fma_f32 v[194:195], v[216:217], v[166:167], v[194:195]
	v_pk_fma_f32 v[194:195], v[218:219], v[168:169], v[194:195]
	v_pk_fma_f32 v[194:195], v[220:221], v[170:171], v[194:195]
	v_pk_fma_f32 v[194:195], v[222:223], v[174:175], v[194:195]
	v_pk_fma_f32 v[194:195], v[224:225], v[176:177], v[194:195]
	v_pk_fma_f32 v[194:195], v[226:227], v[178:179], v[194:195]
	v_pk_fma_f32 v[194:195], v[228:229], v[180:181], v[194:195]
	v_add_f32_e32 v233, v194, v195
	ds_write2st64_b32 v100, v232, v233 offset0:160 offset1:168
	v_pk_fma_f32 v[196:197], v[66:67], v[150:151], v[230:231]
	v_pk_fma_f32 v[196:197], v[68:69], v[152:153], v[196:197]
	v_pk_fma_f32 v[196:197], v[70:71], v[154:155], v[196:197]
	v_pk_fma_f32 v[196:197], v[72:73], v[156:157], v[196:197]
	v_pk_fma_f32 v[196:197], v[74:75], v[158:159], v[196:197]
	v_pk_fma_f32 v[196:197], v[76:77], v[160:161], v[196:197]
	v_pk_fma_f32 v[196:197], v[78:79], v[162:163], v[196:197]
	v_pk_fma_f32 v[196:197], v[80:81], v[164:165], v[196:197]
	v_pk_fma_f32 v[196:197], v[82:83], v[166:167], v[196:197]
	v_pk_fma_f32 v[196:197], v[84:85], v[168:169], v[196:197]
	v_pk_fma_f32 v[196:197], v[86:87], v[170:171], v[196:197]
	v_pk_fma_f32 v[196:197], v[88:89], v[174:175], v[196:197]
	v_pk_fma_f32 v[196:197], v[90:91], v[176:177], v[196:197]
	v_pk_fma_f32 v[196:197], v[92:93], v[178:179], v[196:197]
	v_pk_fma_f32 v[196:197], v[94:95], v[180:181], v[196:197]
	v_fmac_f32_e32 v196, v96, v182
	v_add_f32_e32 v234, v197, v196
	v_fma_f32 v199, v66, v151, v97
	v_mov_b32_e32 v198, 0
	v_pk_fma_f32 v[198:199], v[200:201], v[152:153], v[198:199]
	v_pk_fma_f32 v[198:199], v[202:203], v[154:155], v[198:199]
	v_pk_fma_f32 v[198:199], v[204:205], v[156:157], v[198:199]
	v_pk_fma_f32 v[198:199], v[206:207], v[158:159], v[198:199]
	v_pk_fma_f32 v[198:199], v[208:209], v[160:161], v[198:199]
	v_pk_fma_f32 v[198:199], v[210:211], v[162:163], v[198:199]
	v_pk_fma_f32 v[198:199], v[212:213], v[164:165], v[198:199]
	v_pk_fma_f32 v[198:199], v[214:215], v[166:167], v[198:199]
	v_pk_fma_f32 v[198:199], v[216:217], v[168:169], v[198:199]
	v_pk_fma_f32 v[198:199], v[218:219], v[170:171], v[198:199]
	v_pk_fma_f32 v[198:199], v[220:221], v[174:175], v[198:199]
	v_pk_fma_f32 v[198:199], v[222:223], v[176:177], v[198:199]
	v_pk_fma_f32 v[198:199], v[224:225], v[178:179], v[198:199]
	v_pk_fma_f32 v[198:199], v[226:227], v[180:181], v[198:199]
	v_pk_fma_f32 v[198:199], v[228:229], v[182:183], v[198:199]
	v_add_f32_e32 v235, v198, v199
	ds_write2st64_b32 v100, v234, v235 offset0:176 offset1:184
	v_pk_fma_f32 v[192:193], v[66:67], v[152:153], v[230:231]
	v_pk_fma_f32 v[192:193], v[68:69], v[154:155], v[192:193]
	v_pk_fma_f32 v[192:193], v[70:71], v[156:157], v[192:193]
	v_pk_fma_f32 v[192:193], v[72:73], v[158:159], v[192:193]
	v_pk_fma_f32 v[192:193], v[74:75], v[160:161], v[192:193]
	v_pk_fma_f32 v[192:193], v[76:77], v[162:163], v[192:193]
	v_pk_fma_f32 v[192:193], v[78:79], v[164:165], v[192:193]
	v_pk_fma_f32 v[192:193], v[80:81], v[166:167], v[192:193]
	v_pk_fma_f32 v[192:193], v[82:83], v[168:169], v[192:193]
	v_pk_fma_f32 v[192:193], v[84:85], v[170:171], v[192:193]
	v_pk_fma_f32 v[192:193], v[86:87], v[174:175], v[192:193]
	v_pk_fma_f32 v[192:193], v[88:89], v[176:177], v[192:193]
	v_pk_fma_f32 v[192:193], v[90:91], v[178:179], v[192:193]
	v_pk_fma_f32 v[192:193], v[92:93], v[180:181], v[192:193]
	v_pk_fma_f32 v[192:193], v[94:95], v[182:183], v[192:193]
	v_fmac_f32_e32 v192, v96, v184
	v_add_f32_e32 v232, v193, v192
	v_fma_f32 v195, v66, v153, v97
	v_mov_b32_e32 v194, 0
	v_pk_fma_f32 v[194:195], v[200:201], v[154:155], v[194:195]
	v_pk_fma_f32 v[194:195], v[202:203], v[156:157], v[194:195]
	v_pk_fma_f32 v[194:195], v[204:205], v[158:159], v[194:195]
	v_pk_fma_f32 v[194:195], v[206:207], v[160:161], v[194:195]
	v_pk_fma_f32 v[194:195], v[208:209], v[162:163], v[194:195]
	v_pk_fma_f32 v[194:195], v[210:211], v[164:165], v[194:195]
	v_pk_fma_f32 v[194:195], v[212:213], v[166:167], v[194:195]
	v_pk_fma_f32 v[194:195], v[214:215], v[168:169], v[194:195]
	v_pk_fma_f32 v[194:195], v[216:217], v[170:171], v[194:195]
	v_pk_fma_f32 v[194:195], v[218:219], v[174:175], v[194:195]
	v_pk_fma_f32 v[194:195], v[220:221], v[176:177], v[194:195]
	v_pk_fma_f32 v[194:195], v[222:223], v[178:179], v[194:195]
	v_pk_fma_f32 v[194:195], v[224:225], v[180:181], v[194:195]
	v_pk_fma_f32 v[194:195], v[226:227], v[182:183], v[194:195]
	v_pk_fma_f32 v[194:195], v[228:229], v[184:185], v[194:195]
	v_add_f32_e32 v233, v194, v195
	ds_write2st64_b32 v100, v232, v233 offset0:192 offset1:200
	v_pk_fma_f32 v[196:197], v[66:67], v[154:155], v[230:231]
	v_pk_fma_f32 v[196:197], v[68:69], v[156:157], v[196:197]
	v_pk_fma_f32 v[196:197], v[70:71], v[158:159], v[196:197]
	v_pk_fma_f32 v[196:197], v[72:73], v[160:161], v[196:197]
	v_pk_fma_f32 v[196:197], v[74:75], v[162:163], v[196:197]
	v_pk_fma_f32 v[196:197], v[76:77], v[164:165], v[196:197]
	v_pk_fma_f32 v[196:197], v[78:79], v[166:167], v[196:197]
	v_pk_fma_f32 v[196:197], v[80:81], v[168:169], v[196:197]
	v_pk_fma_f32 v[196:197], v[82:83], v[170:171], v[196:197]
	v_pk_fma_f32 v[196:197], v[84:85], v[174:175], v[196:197]
	v_pk_fma_f32 v[196:197], v[86:87], v[176:177], v[196:197]
	v_pk_fma_f32 v[196:197], v[88:89], v[178:179], v[196:197]
	v_pk_fma_f32 v[196:197], v[90:91], v[180:181], v[196:197]
	v_pk_fma_f32 v[196:197], v[92:93], v[182:183], v[196:197]
	v_pk_fma_f32 v[196:197], v[94:95], v[184:185], v[196:197]
	v_fmac_f32_e32 v196, v96, v186
	v_add_f32_e32 v234, v197, v196
	v_fma_f32 v199, v66, v155, v97
	v_mov_b32_e32 v198, 0
	v_pk_fma_f32 v[198:199], v[200:201], v[156:157], v[198:199]
	v_pk_fma_f32 v[198:199], v[202:203], v[158:159], v[198:199]
	v_pk_fma_f32 v[198:199], v[204:205], v[160:161], v[198:199]
	v_pk_fma_f32 v[198:199], v[206:207], v[162:163], v[198:199]
	v_pk_fma_f32 v[198:199], v[208:209], v[164:165], v[198:199]
	v_pk_fma_f32 v[198:199], v[210:211], v[166:167], v[198:199]
	v_pk_fma_f32 v[198:199], v[212:213], v[168:169], v[198:199]
	v_pk_fma_f32 v[198:199], v[214:215], v[170:171], v[198:199]
	v_pk_fma_f32 v[198:199], v[216:217], v[174:175], v[198:199]
	v_pk_fma_f32 v[198:199], v[218:219], v[176:177], v[198:199]
	v_pk_fma_f32 v[198:199], v[220:221], v[178:179], v[198:199]
	v_pk_fma_f32 v[198:199], v[222:223], v[180:181], v[198:199]
	v_pk_fma_f32 v[198:199], v[224:225], v[182:183], v[198:199]
	v_pk_fma_f32 v[198:199], v[226:227], v[184:185], v[198:199]
	v_pk_fma_f32 v[198:199], v[228:229], v[186:187], v[198:199]
	v_add_f32_e32 v235, v198, v199
	ds_write2st64_b32 v100, v234, v235 offset0:208 offset1:216
	v_pk_fma_f32 v[192:193], v[66:67], v[156:157], v[230:231]
	v_pk_fma_f32 v[192:193], v[68:69], v[158:159], v[192:193]
	v_pk_fma_f32 v[192:193], v[70:71], v[160:161], v[192:193]
	v_pk_fma_f32 v[192:193], v[72:73], v[162:163], v[192:193]
	v_pk_fma_f32 v[192:193], v[74:75], v[164:165], v[192:193]
	v_pk_fma_f32 v[192:193], v[76:77], v[166:167], v[192:193]
	v_pk_fma_f32 v[192:193], v[78:79], v[168:169], v[192:193]
	v_pk_fma_f32 v[192:193], v[80:81], v[170:171], v[192:193]
	v_pk_fma_f32 v[192:193], v[82:83], v[174:175], v[192:193]
	v_pk_fma_f32 v[192:193], v[84:85], v[176:177], v[192:193]
	v_pk_fma_f32 v[192:193], v[86:87], v[178:179], v[192:193]
	v_pk_fma_f32 v[192:193], v[88:89], v[180:181], v[192:193]
	v_pk_fma_f32 v[192:193], v[90:91], v[182:183], v[192:193]
	v_pk_fma_f32 v[192:193], v[92:93], v[184:185], v[192:193]
	v_pk_fma_f32 v[192:193], v[94:95], v[186:187], v[192:193]
	v_fmac_f32_e32 v192, v96, v188
	v_add_f32_e32 v232, v193, v192
	v_fma_f32 v195, v66, v157, v97
	v_mov_b32_e32 v194, 0
	v_pk_fma_f32 v[194:195], v[200:201], v[158:159], v[194:195]
	v_pk_fma_f32 v[194:195], v[202:203], v[160:161], v[194:195]
	v_pk_fma_f32 v[194:195], v[204:205], v[162:163], v[194:195]
	v_pk_fma_f32 v[194:195], v[206:207], v[164:165], v[194:195]
	v_pk_fma_f32 v[194:195], v[208:209], v[166:167], v[194:195]
	v_pk_fma_f32 v[194:195], v[210:211], v[168:169], v[194:195]
	v_pk_fma_f32 v[194:195], v[212:213], v[170:171], v[194:195]
	v_pk_fma_f32 v[194:195], v[214:215], v[174:175], v[194:195]
	v_pk_fma_f32 v[194:195], v[216:217], v[176:177], v[194:195]
	v_pk_fma_f32 v[194:195], v[218:219], v[178:179], v[194:195]
	v_pk_fma_f32 v[194:195], v[220:221], v[180:181], v[194:195]
	v_pk_fma_f32 v[194:195], v[222:223], v[182:183], v[194:195]
	v_pk_fma_f32 v[194:195], v[224:225], v[184:185], v[194:195]
	v_pk_fma_f32 v[194:195], v[226:227], v[186:187], v[194:195]
	v_pk_fma_f32 v[194:195], v[228:229], v[188:189], v[194:195]
	v_add_f32_e32 v233, v194, v195
	ds_write2st64_b32 v100, v232, v233 offset0:224 offset1:232
	v_pk_fma_f32 v[196:197], v[66:67], v[158:159], v[230:231]
	v_pk_fma_f32 v[196:197], v[68:69], v[160:161], v[196:197]
	v_pk_fma_f32 v[196:197], v[70:71], v[162:163], v[196:197]
	v_pk_fma_f32 v[196:197], v[72:73], v[164:165], v[196:197]
	v_pk_fma_f32 v[196:197], v[74:75], v[166:167], v[196:197]
	v_pk_fma_f32 v[196:197], v[76:77], v[168:169], v[196:197]
	v_pk_fma_f32 v[196:197], v[78:79], v[170:171], v[196:197]
	v_pk_fma_f32 v[196:197], v[80:81], v[174:175], v[196:197]
	v_pk_fma_f32 v[196:197], v[82:83], v[176:177], v[196:197]
	v_pk_fma_f32 v[196:197], v[84:85], v[178:179], v[196:197]
	v_pk_fma_f32 v[196:197], v[86:87], v[180:181], v[196:197]
	v_pk_fma_f32 v[196:197], v[88:89], v[182:183], v[196:197]
	v_pk_fma_f32 v[196:197], v[90:91], v[184:185], v[196:197]
	v_pk_fma_f32 v[196:197], v[92:93], v[186:187], v[196:197]
	v_pk_fma_f32 v[196:197], v[94:95], v[188:189], v[196:197]
	v_fmac_f32_e32 v196, v96, v190
	v_add_f32_e32 v234, v197, v196
	v_fma_f32 v199, v66, v159, v97
	v_mov_b32_e32 v198, 0
	v_pk_fma_f32 v[198:199], v[200:201], v[160:161], v[198:199]
	v_pk_fma_f32 v[198:199], v[202:203], v[162:163], v[198:199]
	v_pk_fma_f32 v[198:199], v[204:205], v[164:165], v[198:199]
	v_pk_fma_f32 v[198:199], v[206:207], v[166:167], v[198:199]
	v_pk_fma_f32 v[198:199], v[208:209], v[168:169], v[198:199]
	v_pk_fma_f32 v[198:199], v[210:211], v[170:171], v[198:199]
	v_pk_fma_f32 v[198:199], v[212:213], v[174:175], v[198:199]
	v_pk_fma_f32 v[198:199], v[214:215], v[176:177], v[198:199]
	v_pk_fma_f32 v[198:199], v[216:217], v[178:179], v[198:199]
	v_pk_fma_f32 v[198:199], v[218:219], v[180:181], v[198:199]
	v_pk_fma_f32 v[198:199], v[220:221], v[182:183], v[198:199]
	v_pk_fma_f32 v[198:199], v[222:223], v[184:185], v[198:199]
	v_pk_fma_f32 v[198:199], v[224:225], v[186:187], v[198:199]
	v_pk_fma_f32 v[198:199], v[226:227], v[188:189], v[198:199]
	v_pk_fma_f32 v[198:199], v[228:229], v[190:191], v[198:199]
	v_add_f32_e32 v235, v198, v199
	ds_write2st64_b32 v100, v234, v235 offset0:240 offset1:248
	s_waitcnt lgkmcnt(0)
	s_barrier
	ds_read_b128 v[128:131], v122
	ds_read_b128 v[132:135], v122 offset:16
	s_ashr_i32 s0, s40, 31
	s_lshr_b32 s0, s0, 26
	s_add_i32 s1, s40, s0
	s_waitcnt lgkmcnt(1)
	v_mov_b32_e32 v34, v129
	v_mov_b32_e32 v35, v130
	v_mov_b32_e32 v64, v128
	v_mov_b32_e32 v65, v131
	v_pk_add_f32 v[34:35], v[34:35], v[64:65]
	s_waitcnt lgkmcnt(0)
	v_mov_b32_e32 v64, v134
	v_mov_b32_e32 v65, v132
	v_mov_b32_e32 v136, v135
	v_mov_b32_e32 v137, v133
	v_pk_add_f32 v[64:65], v[64:65], v[136:137]
	v_add_f32_e32 v33, v34, v35
	v_add_f32_e32 v33, v33, v65
	v_add_f32_e32 v33, v64, v33
	ds_bpermute_b32 v34, v101, v33
	s_ashr_i32 s0, s1, 6
	s_and_b32 s1, s1, 0x7ffffc0
	s_sub_i32 s20, s40, s1
	s_ashr_i32 s1, s0, 31
	s_waitcnt lgkmcnt(0)
	v_add_f32_e32 v33, v33, v34
	ds_bpermute_b32 v34, v102, v33
	s_lshl_b32 s33, s20, 5
	s_lshl_b64 s[20:21], s[0:1], 11
	s_waitcnt lgkmcnt(0)
	v_add_f32_e32 v33, v33, v34
	ds_bpermute_b32 v34, v103, v33
	s_waitcnt lgkmcnt(0)
	v_add_f32_e32 v33, v33, v34
	ds_bpermute_b32 v34, v104, v33
	s_waitcnt lgkmcnt(0)
	v_add_f32_e32 v33, v33, v34
	ds_bpermute_b32 v34, v105, v33
	s_waitcnt lgkmcnt(0)
	v_add_f32_e32 v33, v33, v34
	ds_bpermute_b32 v34, v106, v33
	s_waitcnt lgkmcnt(0)
	v_add_f32_e32 v33, v33, v34
	v_fmamk_f32 v35, v33, 0xbb000000, v131
	v_fmac_f32_e32 v129, 0xbb000000, v33
	v_fmamk_f32 v34, v33, 0xbb000000, v130
	v_fmamk_f32 v128, v33, 0xbb000000, v128
	v_fmamk_f32 v65, v33, 0xbb000000, v133
	v_fmamk_f32 v64, v33, 0xbb000000, v132
	v_fmamk_f32 v135, v33, 0xbb000000, v135
	v_fmac_f32_e32 v134, 0xbb000000, v33
	v_mul_f32_e32 v33, v129, v129
	v_mul_f32_e32 v130, v35, v35
	v_fmac_f32_e32 v33, v128, v128
	v_fmac_f32_e32 v130, v34, v34
	v_add_f32_e32 v33, v33, v130
	v_pk_mul_f32 v[130:131], v[134:135], v[134:135]
	v_pk_mul_f32 v[132:133], v[64:65], v[64:65]
	v_mov_b32_e32 v136, v130
	v_mov_b32_e32 v137, v132
	v_mov_b32_e32 v132, v131
	v_pk_add_f32 v[130:131], v[136:137], v[132:133]
	s_nop 0
	v_add_f32_e32 v33, v131, v33
	v_add_f32_e32 v33, v130, v33
	ds_bpermute_b32 v130, v101, v33
	s_waitcnt lgkmcnt(0)
	v_add_f32_e32 v33, v33, v130
	ds_bpermute_b32 v130, v102, v33
	s_waitcnt lgkmcnt(0)
	v_add_f32_e32 v33, v33, v130
	ds_bpermute_b32 v130, v103, v33
	s_waitcnt lgkmcnt(0)
	v_add_f32_e32 v33, v33, v130
	ds_bpermute_b32 v130, v104, v33
	s_waitcnt lgkmcnt(0)
	v_add_f32_e32 v33, v33, v130
	ds_bpermute_b32 v130, v105, v33
	s_waitcnt lgkmcnt(0)
	v_add_f32_e32 v33, v33, v130
	ds_bpermute_b32 v130, v106, v33
	s_waitcnt lgkmcnt(0)
	v_add_f32_e32 v33, v33, v130
	v_fmamk_f32 v33, v33, 0x3b000000, v123
	v_mul_f32_e32 v130, 0x4f800000, v33
	v_cmp_gt_f32_e32 vcc, s45, v33
	s_nop 1
	v_cndmask_b32_e32 v33, v33, v130, vcc
	v_sqrt_f32_e32 v130, v33
	s_nop 0
	v_add_u32_e32 v131, -1, v130
	v_fma_f32 v132, -v131, v130, v33
	v_cmp_ge_f32_e64 s[0:1], 0, v132
	v_add_u32_e32 v132, 1, v130
	s_nop 0
	v_cndmask_b32_e64 v131, v130, v131, s[0:1]
	v_fma_f32 v130, -v132, v130, v33
	v_cmp_lt_f32_e64 s[0:1], 0, v130
	s_nop 1
	v_cndmask_b32_e64 v130, v131, v132, s[0:1]
	v_mul_f32_e32 v131, 0x37800000, v130
	v_cndmask_b32_e32 v130, v130, v131, vcc
	v_cmp_class_f32_e32 vcc, v33, v124
	s_nop 1
	v_cndmask_b32_e32 v33, v130, v33, vcc
	v_div_scale_f32 v130, s[0:1], v33, v33, 1.0
	v_rcp_f32_e32 v131, v130
	s_ashr_i32 s0, s33, 31
	s_add_u32 s40, s20, s33
	s_addc_u32 s41, s21, s0
	v_fma_f32 v132, -v130, v131, 1.0
	v_fmac_f32_e32 v131, v132, v131
	v_div_scale_f32 v132, vcc, 1.0, v33, 1.0
	v_mul_f32_e32 v133, v132, v131
	v_fma_f32 v136, -v130, v133, v132
	v_fmac_f32_e32 v133, v136, v131
	v_fma_f32 v130, -v130, v133, v132
	v_div_fmas_f32 v130, v130, v131, v133
	v_div_fixup_f32 v130, v130, v33, 1.0
	v_pk_mul_f32 v[128:129], v[128:129], v[130:131] op_sel_hi:[1,0]
	v_pk_mul_f32 v[64:65], v[64:65], v[130:131] op_sel_hi:[1,0]
	s_waitcnt vmcnt(0)
	v_pk_fma_f32 v[136:137], v[8:9], v[128:129], v[12:13]
	v_pk_mul_f32 v[128:129], v[134:135], v[130:131] op_sel_hi:[1,0]
	v_pk_fma_f32 v[64:65], v[0:1], v[64:65], v[4:5]
	v_mul_f32_e32 v33, 0xbfb8aa3b, v136
	v_pk_mul_f32 v[34:35], v[34:35], v[130:131] op_sel_hi:[1,0]
	v_exp_f32_e32 v33, v33
	v_mul_f32_e32 v130, 0xbfb8aa3b, v64
	v_pk_fma_f32 v[138:139], v[2:3], v[128:129], v[6:7]
	v_mul_f32_e32 v128, 0xbfb8aa3b, v137
	v_exp_f32_e32 v130, v130
	v_exp_f32_e32 v128, v128
	v_add_f32_e32 v33, 1.0, v33
	v_rcp_f32_e32 v140, v33
	v_add_f32_e32 v33, 1.0, v130
	v_add_f32_e32 v132, 1.0, v128
	ds_read_b128 v[128:131], v125
	v_rcp_f32_e32 v142, v33
	v_mul_f32_e32 v33, 0xbfb8aa3b, v65
	v_rcp_f32_e32 v144, v132
	ds_read_b128 v[132:135], v125 offset:16
	v_exp_f32_e32 v33, v33
	s_waitcnt lgkmcnt(1)
	v_mov_b32_e32 v148, v129
	v_mov_b32_e32 v149, v130
	v_mov_b32_e32 v150, v128
	v_mov_b32_e32 v151, v131
	v_add_f32_e32 v33, 1.0, v33
	v_pk_add_f32 v[148:149], v[148:149], v[150:151]
	s_waitcnt lgkmcnt(0)
	v_mov_b32_e32 v150, v134
	v_mov_b32_e32 v151, v132
	v_mov_b32_e32 v152, v135
	v_mov_b32_e32 v153, v133
	v_rcp_f32_e32 v146, v33
	v_pk_add_f32 v[150:151], v[150:151], v[152:153]
	v_add_f32_e32 v33, v148, v149
	v_add_f32_e32 v33, v33, v151
	v_add_f32_e32 v33, v150, v33
	ds_bpermute_b32 v141, v101, v33
	v_pk_fma_f32 v[34:35], v[10:11], v[34:35], v[14:15]
	v_mul_f32_e32 v145, 0xbfb8aa3b, v138
	v_mul_f32_e32 v143, 0xbfb8aa3b, v34
	v_exp_f32_e32 v143, v143
	s_waitcnt lgkmcnt(0)
	v_add_f32_e32 v33, v33, v141
	ds_bpermute_b32 v147, v102, v33
	v_exp_f32_e32 v145, v145
	v_add_f32_e32 v141, 1.0, v143
	v_mul_f32_e32 v148, 0xbfb8aa3b, v139
	v_exp_f32_e32 v148, v148
	s_waitcnt lgkmcnt(0)
	v_add_f32_e32 v33, v33, v147
	v_add_f32_e32 v143, 1.0, v145
	ds_bpermute_b32 v145, v103, v33
	v_mul_f32_e32 v147, 0xbfb8aa3b, v35
	v_exp_f32_e32 v147, v147
	v_rcp_f32_e32 v141, v141
	v_rcp_f32_e32 v143, v143
	s_waitcnt lgkmcnt(0)
	v_add_f32_e32 v33, v33, v145
	ds_bpermute_b32 v149, v104, v33
	v_add_f32_e32 v145, 1.0, v147
	v_add_f32_e32 v147, 1.0, v148
	v_mov_b32_e32 v148, v136
	v_rcp_f32_e32 v145, v145
	s_waitcnt lgkmcnt(0)
	v_add_f32_e32 v33, v33, v149
	ds_bpermute_b32 v150, v105, v33
	v_mov_b32_e32 v149, v34
	v_pk_mul_f32 v[140:141], v[148:149], v[140:141]
	v_mov_b32_e32 v34, v137
	v_mov_b32_e32 v136, v64
	s_waitcnt lgkmcnt(0)
	v_add_f32_e32 v33, v33, v150
	ds_bpermute_b32 v148, v106, v33
	v_mov_b32_e32 v137, v138
	v_pk_mul_f32 v[34:35], v[34:35], v[144:145]
	v_pk_mul_f32 v[136:137], v[136:137], v[142:143]
	v_rcp_f32_e32 v147, v147
	s_waitcnt lgkmcnt(0)
	v_add_f32_e32 v33, v33, v148
	v_fmamk_f32 v143, v33, 0xbb000000, v131
	v_fmac_f32_e32 v129, 0xbb000000, v33
	v_fmamk_f32 v145, v33, 0xbb000000, v133
	v_fmamk_f32 v144, v33, 0xbb000000, v132
	v_fmamk_f32 v135, v33, 0xbb000000, v135
	v_fmac_f32_e32 v134, 0xbb000000, v33
	v_fmamk_f32 v142, v33, 0xbb000000, v130
	v_fmamk_f32 v128, v33, 0xbb000000, v128
	v_mul_f32_e32 v33, v129, v129
	v_mul_f32_e32 v64, v143, v143
	v_pk_mul_f32 v[130:131], v[134:135], v[134:135]
	v_pk_mul_f32 v[132:133], v[144:145], v[144:145]
	v_fmac_f32_e32 v33, v128, v128
	v_fmac_f32_e32 v64, v142, v142
	v_mov_b32_e32 v148, v130
	v_mov_b32_e32 v149, v132
	v_mov_b32_e32 v132, v131
	v_add_f32_e32 v33, v33, v64
	v_pk_add_f32 v[130:131], v[148:149], v[132:133]
	v_mov_b32_e32 v138, v65
	v_add_f32_e32 v33, v131, v33
	v_add_f32_e32 v33, v130, v33
	ds_bpermute_b32 v130, v101, v33
	v_pk_mul_f32 v[64:65], v[138:139], v[146:147]
	v_bfe_u32 v133, v35, 16, 1
	v_bfe_u32 v131, v65, 16, 1
	v_bfe_u32 v132, v64, 16, 1
	s_waitcnt lgkmcnt(0)
	v_add_f32_e32 v33, v33, v130
	ds_bpermute_b32 v130, v102, v33
	v_add3_u32 v35, v35, v133, s52
	v_add3_u32 v64, v64, v132, s52
	v_add3_u32 v65, v65, v131, s52
	v_bfe_u32 v131, v140, 16, 1
	s_waitcnt lgkmcnt(0)
	v_add_f32_e32 v33, v33, v130
	ds_bpermute_b32 v130, v103, v33
	v_bfe_u32 v132, v141, 16, 1
	v_bfe_u32 v133, v136, 16, 1
	v_add3_u32 v133, v136, v133, s52
	v_add3_u32 v132, v141, v132, s52
	s_waitcnt lgkmcnt(0)
	v_add_f32_e32 v33, v33, v130
	ds_bpermute_b32 v130, v104, v33
	v_add3_u32 v131, v140, v131, s52
	v_lshrrev_b32_e32 v136, 16, v131
	v_lshrrev_b32_e32 v131, 16, v132
	v_lshrrev_b32_e32 v132, 16, v133
	s_waitcnt lgkmcnt(0)
	v_add_f32_e32 v33, v33, v130
	ds_bpermute_b32 v130, v105, v33
	v_and_or_b32 v132, v64, s53, v132
	v_bfe_u32 v138, v34, 16, 1
	v_add3_u32 v34, v34, v138, s52
	v_bfe_u32 v138, v137, 16, 1
	s_waitcnt lgkmcnt(0)
	v_add_f32_e32 v33, v33, v130
	ds_bpermute_b32 v130, v106, v33
	v_add3_u32 v137, v137, v138, s52
	v_lshrrev_b32_e32 v133, 16, v137
	v_and_or_b32 v133, v65, s53, v133
	v_and_or_b32 v131, v35, s53, v131
	s_waitcnt lgkmcnt(0)
	v_add_f32_e32 v33, v33, v130
	v_fmamk_f32 v33, v33, 0x3b000000, v123
	v_mul_f32_e32 v64, 0x4f800000, v33
	v_cmp_gt_f32_e32 vcc, s45, v33
	v_and_or_b32 v130, v34, s53, v136
	v_lshl_add_u64 v[34:35], s[40:41], 0, v[54:55]
	v_cndmask_b32_e32 v33, v33, v64, vcc
	v_sqrt_f32_e32 v64, v33
	v_lshlrev_b64 v[34:35], 11, v[34:35]
	v_lshl_add_u64 v[34:35], v[62:63], 0, v[34:35]
	global_store_dwordx4 v[34:35], v[130:133], off offset:1024
	v_add_u32_e32 v65, -1, v64
	v_fma_f32 v136, -v65, v64, v33
	v_cmp_ge_f32_e64 s[0:1], 0, v136
	v_add_u32_e32 v136, 1, v64
	s_add_i32 s43, s43, 32
	v_cndmask_b32_e64 v65, v64, v65, s[0:1]
	v_fma_f32 v64, -v136, v64, v33
	v_cmp_lt_f32_e64 s[0:1], 0, v64
	s_cmp_lg_u32 s42, s44
	s_nop 0
	v_cndmask_b32_e64 v64, v65, v136, s[0:1]
	v_mul_f32_e32 v65, 0x37800000, v64
	v_cndmask_b32_e32 v64, v64, v65, vcc
	v_cmp_class_f32_e32 vcc, v33, v124
	s_nop 1
	v_cndmask_b32_e32 v33, v64, v33, vcc
	v_div_scale_f32 v64, s[0:1], v33, v33, 1.0
	v_rcp_f32_e32 v65, v64
	s_nop 0
	v_fma_f32 v34, -v64, v65, 1.0
	v_fmac_f32_e32 v65, v34, v65
	v_div_scale_f32 v34, vcc, 1.0, v33, 1.0
	v_mul_f32_e32 v35, v34, v65
	v_fma_f32 v130, -v64, v35, v34
	v_fmac_f32_e32 v35, v130, v65
	v_fma_f32 v34, -v64, v35, v34
	v_div_fmas_f32 v34, v34, v65, v35
	v_div_fixup_f32 v34, v34, v33, 1.0
	v_pk_mul_f32 v[64:65], v[128:129], v[34:35] op_sel_hi:[1,0]
	v_pk_mul_f32 v[128:129], v[142:143], v[34:35] op_sel_hi:[1,0]
	v_pk_fma_f32 v[64:65], v[8:9], v[64:65], v[12:13]
	v_pk_fma_f32 v[136:137], v[10:11], v[128:129], v[14:15]
	v_pk_mul_f32 v[128:129], v[144:145], v[34:35] op_sel_hi:[1,0]
	v_mul_f32_e32 v33, 0xbfb8aa3b, v64
	v_pk_fma_f32 v[138:139], v[0:1], v[128:129], v[4:5]
	v_exp_f32_e32 v33, v33
	v_mul_f32_e32 v128, 0xbfb8aa3b, v138
	v_exp_f32_e32 v128, v128
	v_pk_mul_f32 v[34:35], v[134:135], v[34:35] op_sel_hi:[1,0]
	v_add_f32_e32 v33, 1.0, v33
	v_rcp_f32_e32 v140, v33
	v_add_f32_e32 v33, 1.0, v128
	v_mul_f32_e32 v128, 0xbfb8aa3b, v65
	v_exp_f32_e32 v128, v128
	v_rcp_f32_e32 v142, v33
	v_mul_f32_e32 v33, 0xbfb8aa3b, v139
	v_exp_f32_e32 v33, v33
	v_add_f32_e32 v132, 1.0, v128
	ds_read_b128 v[128:131], v126
	v_rcp_f32_e32 v144, v132
	ds_read_b128 v[132:135], v126 offset:16
	v_add_f32_e32 v33, 1.0, v33
	v_rcp_f32_e32 v146, v33
	s_waitcnt lgkmcnt(1)
	v_mov_b32_e32 v148, v129
	v_mov_b32_e32 v149, v130
	v_mov_b32_e32 v150, v128
	v_mov_b32_e32 v151, v131
	v_pk_add_f32 v[148:149], v[148:149], v[150:151]
	s_waitcnt lgkmcnt(0)
	v_mov_b32_e32 v150, v134
	v_mov_b32_e32 v151, v132
	v_mov_b32_e32 v152, v135
	v_mov_b32_e32 v153, v133
	v_pk_add_f32 v[150:151], v[150:151], v[152:153]
	v_add_f32_e32 v33, v148, v149
	v_add_f32_e32 v33, v33, v151
	v_add_f32_e32 v33, v150, v33
	ds_bpermute_b32 v141, v101, v33
	v_pk_fma_f32 v[34:35], v[2:3], v[34:35], v[6:7]
	v_mul_f32_e32 v143, 0xbfb8aa3b, v136
	v_mul_f32_e32 v145, 0xbfb8aa3b, v34
	v_exp_f32_e32 v143, v143
	s_waitcnt lgkmcnt(0)
	v_add_f32_e32 v33, v33, v141
	ds_bpermute_b32 v147, v102, v33
	v_exp_f32_e32 v145, v145
	v_add_f32_e32 v141, 1.0, v143
	v_mul_f32_e32 v148, 0xbfb8aa3b, v35
	v_exp_f32_e32 v148, v148
	s_waitcnt lgkmcnt(0)
	v_add_f32_e32 v33, v33, v147
	v_add_f32_e32 v143, 1.0, v145
	ds_bpermute_b32 v145, v103, v33
	v_mul_f32_e32 v147, 0xbfb8aa3b, v137
	v_exp_f32_e32 v147, v147
	v_rcp_f32_e32 v141, v141
	v_rcp_f32_e32 v143, v143
	s_waitcnt lgkmcnt(0)
	v_add_f32_e32 v33, v33, v145
	ds_bpermute_b32 v149, v104, v33
	v_add_f32_e32 v145, 1.0, v147
	v_add_f32_e32 v147, 1.0, v148
	v_mov_b32_e32 v148, v64
	v_rcp_f32_e32 v145, v145
	s_waitcnt lgkmcnt(0)
	v_add_f32_e32 v33, v33, v149
	ds_bpermute_b32 v150, v105, v33
	v_mov_b32_e32 v149, v136
	v_pk_mul_f32 v[140:141], v[148:149], v[140:141]
	v_mov_b32_e32 v136, v65
	v_pk_mul_f32 v[64:65], v[136:137], v[144:145]
	s_waitcnt lgkmcnt(0)
	v_add_f32_e32 v33, v33, v150
	ds_bpermute_b32 v148, v106, v33
	v_mov_b32_e32 v136, v138
	v_mov_b32_e32 v137, v34
	v_pk_mul_f32 v[136:137], v[136:137], v[142:143]
	v_rcp_f32_e32 v147, v147
	s_waitcnt lgkmcnt(0)
	v_add_f32_e32 v33, v33, v148
	v_fmamk_f32 v143, v33, 0xbb000000, v131
	v_fmac_f32_e32 v129, 0xbb000000, v33
	v_fmamk_f32 v145, v33, 0xbb000000, v133
	v_fmamk_f32 v144, v33, 0xbb000000, v132
	v_fmamk_f32 v135, v33, 0xbb000000, v135
	v_fmac_f32_e32 v134, 0xbb000000, v33
	v_fmamk_f32 v142, v33, 0xbb000000, v130
	v_fmamk_f32 v128, v33, 0xbb000000, v128
	v_mul_f32_e32 v33, v129, v129
	v_mul_f32_e32 v34, v143, v143
	v_pk_mul_f32 v[130:131], v[134:135], v[134:135]
	v_pk_mul_f32 v[132:133], v[144:145], v[144:145]
	v_fmac_f32_e32 v33, v128, v128
	v_fmac_f32_e32 v34, v142, v142
	v_mov_b32_e32 v148, v130
	v_mov_b32_e32 v149, v132
	v_mov_b32_e32 v132, v131
	v_add_f32_e32 v33, v33, v34
	v_pk_add_f32 v[130:131], v[148:149], v[132:133]
	v_mov_b32_e32 v34, v139
	v_add_f32_e32 v33, v131, v33
	v_add_f32_e32 v33, v130, v33
	ds_bpermute_b32 v130, v101, v33
	v_pk_mul_f32 v[34:35], v[34:35], v[146:147]
	v_bfe_u32 v133, v65, 16, 1
	v_bfe_u32 v131, v35, 16, 1
	v_bfe_u32 v132, v34, 16, 1
	s_waitcnt lgkmcnt(0)
	v_add_f32_e32 v33, v33, v130
	ds_bpermute_b32 v130, v102, v33
	v_add3_u32 v65, v65, v133, s52
	v_add3_u32 v34, v34, v132, s52
	v_add3_u32 v35, v35, v131, s52
	v_bfe_u32 v131, v140, 16, 1
	s_waitcnt lgkmcnt(0)
	v_add_f32_e32 v33, v33, v130
	ds_bpermute_b32 v130, v103, v33
	v_bfe_u32 v132, v141, 16, 1
	v_bfe_u32 v133, v136, 16, 1
	v_add3_u32 v133, v136, v133, s52
	v_add3_u32 v132, v141, v132, s52
	s_waitcnt lgkmcnt(0)
	v_add_f32_e32 v33, v33, v130
	ds_bpermute_b32 v130, v104, v33
	v_add3_u32 v131, v140, v131, s52
	v_bfe_u32 v138, v64, 16, 1
	v_lshrrev_b32_e32 v136, 16, v131
	v_lshrrev_b32_e32 v131, 16, v132
	s_waitcnt lgkmcnt(0)
	v_add_f32_e32 v33, v33, v130
	ds_bpermute_b32 v130, v105, v33
	v_lshrrev_b32_e32 v132, 16, v133
	v_add3_u32 v64, v64, v138, s52
	v_bfe_u32 v138, v137, 16, 1
	v_and_or_b32 v132, v34, s53, v132
	s_waitcnt lgkmcnt(0)
	v_add_f32_e32 v33, v33, v130
	ds_bpermute_b32 v130, v106, v33
	v_add3_u32 v137, v137, v138, s52
	v_lshrrev_b32_e32 v133, 16, v137
	v_and_or_b32 v131, v65, s53, v131
	v_and_or_b32 v133, v35, s53, v133
	s_waitcnt lgkmcnt(0)
	v_add_f32_e32 v33, v33, v130
	v_fmamk_f32 v33, v33, 0x3b000000, v123
	v_mul_f32_e32 v34, 0x4f800000, v33
	v_cmp_gt_f32_e32 vcc, s45, v33
	v_and_or_b32 v130, v64, s53, v136
	s_nop 0
	v_cndmask_b32_e32 v33, v33, v34, vcc
	v_sqrt_f32_e32 v137, v33
	v_lshl_add_u64 v[34:35], s[40:41], 0, v[56:57]
	v_lshlrev_b64 v[34:35], 11, v[34:35]
	v_lshl_add_u64 v[34:35], v[62:63], 0, v[34:35]
	v_add_u32_e32 v64, -1, v137
	v_fma_f32 v65, -v64, v137, v33
	v_cmp_ge_f32_e64 s[0:1], 0, v65
	v_add_u32_e32 v65, 1, v137
	v_fma_f32 v136, -v65, v137, v33
	v_cndmask_b32_e64 v64, v137, v64, s[0:1]
	v_cmp_lt_f32_e64 s[0:1], 0, v136
	global_store_dwordx4 v[34:35], v[130:133], off offset:1024
	s_nop 0
	v_cndmask_b32_e64 v64, v64, v65, s[0:1]
	v_mul_f32_e32 v65, 0x37800000, v64
	v_cndmask_b32_e32 v64, v64, v65, vcc
	v_cmp_class_f32_e32 vcc, v33, v124
	s_nop 1
	v_cndmask_b32_e32 v33, v64, v33, vcc
	v_div_scale_f32 v64, s[0:1], v33, v33, 1.0
	v_rcp_f32_e32 v65, v64
	s_nop 0
	v_fma_f32 v34, -v64, v65, 1.0
	v_fmac_f32_e32 v65, v34, v65
	v_div_scale_f32 v34, vcc, 1.0, v33, 1.0
	v_mul_f32_e32 v35, v34, v65
	v_fma_f32 v130, -v64, v35, v34
	v_fmac_f32_e32 v35, v130, v65
	v_fma_f32 v34, -v64, v35, v34
	v_div_fmas_f32 v34, v34, v65, v35
	v_div_fixup_f32 v34, v34, v33, 1.0
	v_pk_mul_f32 v[64:65], v[128:129], v[34:35] op_sel_hi:[1,0]
	v_pk_mul_f32 v[128:129], v[142:143], v[34:35] op_sel_hi:[1,0]
	v_pk_fma_f32 v[64:65], v[8:9], v[64:65], v[12:13]
	v_pk_fma_f32 v[136:137], v[10:11], v[128:129], v[14:15]
	v_pk_mul_f32 v[128:129], v[144:145], v[34:35] op_sel_hi:[1,0]
	v_mul_f32_e32 v33, 0xbfb8aa3b, v64
	v_pk_fma_f32 v[138:139], v[0:1], v[128:129], v[4:5]
	v_exp_f32_e32 v33, v33
	v_mul_f32_e32 v128, 0xbfb8aa3b, v138
	v_exp_f32_e32 v128, v128
	v_pk_mul_f32 v[34:35], v[134:135], v[34:35] op_sel_hi:[1,0]
	v_add_f32_e32 v33, 1.0, v33
	v_rcp_f32_e32 v140, v33
	v_add_f32_e32 v33, 1.0, v128
	v_mul_f32_e32 v128, 0xbfb8aa3b, v65
	v_exp_f32_e32 v128, v128
	v_rcp_f32_e32 v142, v33
	v_mul_f32_e32 v33, 0xbfb8aa3b, v139
	v_exp_f32_e32 v33, v33
	v_add_f32_e32 v132, 1.0, v128
	ds_read_b128 v[128:131], v127
	v_rcp_f32_e32 v144, v132
	ds_read_b128 v[132:135], v127 offset:16
	v_add_f32_e32 v33, 1.0, v33
	v_rcp_f32_e32 v146, v33
	s_waitcnt lgkmcnt(1)
	v_mov_b32_e32 v148, v129
	v_mov_b32_e32 v149, v130
	v_mov_b32_e32 v150, v128
	v_mov_b32_e32 v151, v131
	v_pk_add_f32 v[148:149], v[148:149], v[150:151]
	s_waitcnt lgkmcnt(0)
	v_mov_b32_e32 v150, v134
	v_mov_b32_e32 v151, v132
	v_mov_b32_e32 v152, v135
	v_mov_b32_e32 v153, v133
	v_pk_add_f32 v[150:151], v[150:151], v[152:153]
	v_add_f32_e32 v33, v148, v149
	v_add_f32_e32 v33, v33, v151
	v_add_f32_e32 v33, v150, v33
	ds_bpermute_b32 v141, v101, v33
	v_pk_fma_f32 v[34:35], v[2:3], v[34:35], v[6:7]
	v_mul_f32_e32 v143, 0xbfb8aa3b, v136
	v_mul_f32_e32 v145, 0xbfb8aa3b, v34
	v_exp_f32_e32 v143, v143
	s_waitcnt lgkmcnt(0)
	v_add_f32_e32 v33, v33, v141
	ds_bpermute_b32 v147, v102, v33
	v_exp_f32_e32 v145, v145
	v_add_f32_e32 v141, 1.0, v143
	v_mul_f32_e32 v148, 0xbfb8aa3b, v35
	v_exp_f32_e32 v148, v148
	s_waitcnt lgkmcnt(0)
	v_add_f32_e32 v33, v33, v147
	v_add_f32_e32 v143, 1.0, v145
	ds_bpermute_b32 v145, v103, v33
	v_mul_f32_e32 v147, 0xbfb8aa3b, v137
	v_exp_f32_e32 v147, v147
	v_rcp_f32_e32 v141, v141
	v_rcp_f32_e32 v143, v143
	s_waitcnt lgkmcnt(0)
	v_add_f32_e32 v33, v33, v145
	ds_bpermute_b32 v149, v104, v33
	v_add_f32_e32 v145, 1.0, v147
	v_add_f32_e32 v147, 1.0, v148
	v_mov_b32_e32 v148, v64
	v_rcp_f32_e32 v145, v145
	s_waitcnt lgkmcnt(0)
	v_add_f32_e32 v33, v33, v149
	ds_bpermute_b32 v150, v105, v33
	v_mov_b32_e32 v149, v136
	v_pk_mul_f32 v[140:141], v[148:149], v[140:141]
	v_mov_b32_e32 v136, v65
	v_pk_mul_f32 v[64:65], v[136:137], v[144:145]
	s_waitcnt lgkmcnt(0)
	v_add_f32_e32 v33, v33, v150
	ds_bpermute_b32 v148, v106, v33
	v_mov_b32_e32 v136, v138
	v_mov_b32_e32 v137, v34
	v_pk_mul_f32 v[136:137], v[136:137], v[142:143]
	v_rcp_f32_e32 v147, v147
	s_waitcnt lgkmcnt(0)
	v_add_f32_e32 v33, v33, v148
	v_fmamk_f32 v143, v33, 0xbb000000, v131
	v_fmac_f32_e32 v129, 0xbb000000, v33
	v_fmamk_f32 v145, v33, 0xbb000000, v133
	v_fmamk_f32 v144, v33, 0xbb000000, v132
	v_fmamk_f32 v135, v33, 0xbb000000, v135
	v_fmac_f32_e32 v134, 0xbb000000, v33
	v_fmamk_f32 v142, v33, 0xbb000000, v130
	v_fmamk_f32 v128, v33, 0xbb000000, v128
	v_mul_f32_e32 v33, v129, v129
	v_mul_f32_e32 v34, v143, v143
	v_pk_mul_f32 v[130:131], v[134:135], v[134:135]
	v_pk_mul_f32 v[132:133], v[144:145], v[144:145]
	v_fmac_f32_e32 v33, v128, v128
	v_fmac_f32_e32 v34, v142, v142
	v_mov_b32_e32 v148, v130
	v_mov_b32_e32 v149, v132
	v_mov_b32_e32 v132, v131
	v_add_f32_e32 v33, v33, v34
	v_pk_add_f32 v[130:131], v[148:149], v[132:133]
	v_mov_b32_e32 v34, v139
	v_add_f32_e32 v33, v131, v33
	v_add_f32_e32 v33, v130, v33
	ds_bpermute_b32 v130, v101, v33
	v_pk_mul_f32 v[34:35], v[34:35], v[146:147]
	v_bfe_u32 v133, v65, 16, 1
	v_bfe_u32 v131, v35, 16, 1
	v_bfe_u32 v132, v34, 16, 1
	s_waitcnt lgkmcnt(0)
	v_add_f32_e32 v33, v33, v130
	ds_bpermute_b32 v130, v102, v33
	v_add3_u32 v65, v65, v133, s52
	v_add3_u32 v34, v34, v132, s52
	v_add3_u32 v35, v35, v131, s52
	v_bfe_u32 v131, v140, 16, 1
	s_waitcnt lgkmcnt(0)
	v_add_f32_e32 v33, v33, v130
	ds_bpermute_b32 v130, v103, v33
	v_bfe_u32 v132, v141, 16, 1
	v_bfe_u32 v133, v136, 16, 1
	v_add3_u32 v133, v136, v133, s52
	v_add3_u32 v132, v141, v132, s52
	s_waitcnt lgkmcnt(0)
	v_add_f32_e32 v33, v33, v130
	ds_bpermute_b32 v130, v104, v33
	v_add3_u32 v131, v140, v131, s52
	v_bfe_u32 v138, v64, 16, 1
	v_lshrrev_b32_e32 v136, 16, v131
	v_lshrrev_b32_e32 v131, 16, v132
	s_waitcnt lgkmcnt(0)
	v_add_f32_e32 v33, v33, v130
	ds_bpermute_b32 v130, v105, v33
	v_lshrrev_b32_e32 v132, 16, v133
	v_add3_u32 v64, v64, v138, s52
	v_bfe_u32 v138, v137, 16, 1
	v_and_or_b32 v132, v34, s53, v132
	s_waitcnt lgkmcnt(0)
	v_add_f32_e32 v33, v33, v130
	ds_bpermute_b32 v130, v106, v33
	v_add3_u32 v137, v137, v138, s52
	v_lshrrev_b32_e32 v133, 16, v137
	v_and_or_b32 v131, v65, s53, v131
	v_and_or_b32 v133, v35, s53, v133
	s_waitcnt lgkmcnt(0)
	v_add_f32_e32 v33, v33, v130
	v_fmamk_f32 v33, v33, 0x3b000000, v123
	v_mul_f32_e32 v34, 0x4f800000, v33
	v_cmp_gt_f32_e32 vcc, s45, v33
	v_and_or_b32 v130, v64, s53, v136
	s_nop 0
	v_cndmask_b32_e32 v33, v33, v34, vcc
	v_sqrt_f32_e32 v137, v33
	v_lshl_add_u64 v[34:35], s[40:41], 0, v[58:59]
	v_lshlrev_b64 v[34:35], 11, v[34:35]
	v_lshl_add_u64 v[34:35], v[62:63], 0, v[34:35]
	v_add_u32_e32 v64, -1, v137
	v_fma_f32 v65, -v64, v137, v33
	v_cmp_ge_f32_e64 s[0:1], 0, v65
	v_add_u32_e32 v65, 1, v137
	v_fma_f32 v136, -v65, v137, v33
	v_cndmask_b32_e64 v64, v137, v64, s[0:1]
	v_cmp_lt_f32_e64 s[0:1], 0, v136
	global_store_dwordx4 v[34:35], v[130:133], off offset:1024
	s_nop 0
	v_cndmask_b32_e64 v64, v64, v65, s[0:1]
	v_mul_f32_e32 v65, 0x37800000, v64
	v_cndmask_b32_e32 v64, v64, v65, vcc
	v_cmp_class_f32_e32 vcc, v33, v124
	s_nop 1
	v_cndmask_b32_e32 v33, v64, v33, vcc
	v_div_scale_f32 v64, s[0:1], v33, v33, 1.0
	v_rcp_f32_e32 v65, v64
	s_nop 0
	v_fma_f32 v34, -v64, v65, 1.0
	v_fmac_f32_e32 v65, v34, v65
	v_div_scale_f32 v34, vcc, 1.0, v33, 1.0
	v_mul_f32_e32 v35, v34, v65
	v_fma_f32 v130, -v64, v35, v34
	v_fmac_f32_e32 v35, v130, v65
	v_fma_f32 v34, -v64, v35, v34
	v_div_fmas_f32 v34, v34, v65, v35
	v_div_fixup_f32 v34, v34, v33, 1.0
	v_pk_mul_f32 v[64:65], v[128:129], v[34:35] op_sel_hi:[1,0]
	v_pk_mul_f32 v[130:131], v[144:145], v[34:35] op_sel_hi:[1,0]
	v_pk_fma_f32 v[64:65], v[8:9], v[64:65], v[12:13]
	v_pk_fma_f32 v[130:131], v[0:1], v[130:131], v[4:5]
	v_mul_f32_e32 v33, 0xbfb8aa3b, v64
	v_exp_f32_e32 v33, v33
	v_mul_f32_e32 v132, 0xbfb8aa3b, v130
	v_exp_f32_e32 v133, v132
	v_pk_mul_f32 v[128:129], v[142:143], v[34:35] op_sel_hi:[1,0]
	v_add_f32_e32 v33, 1.0, v33
	v_rcp_f32_e32 v132, v33
	v_add_f32_e32 v33, 1.0, v133
	v_mul_f32_e32 v133, 0xbfb8aa3b, v65
	v_pk_mul_f32 v[34:35], v[134:135], v[34:35] op_sel_hi:[1,0]
	v_exp_f32_e32 v133, v133
	v_mul_f32_e32 v134, 0xbfb8aa3b, v131
	v_exp_f32_e32 v135, v134
	v_pk_fma_f32 v[128:129], v[10:11], v[128:129], v[14:15]
	v_pk_fma_f32 v[34:35], v[2:3], v[34:35], v[6:7]
	v_rcp_f32_e32 v134, v33
	v_add_f32_e32 v33, 1.0, v133
	v_mul_f32_e32 v133, 0xbfb8aa3b, v128
	v_rcp_f32_e32 v136, v33
	v_add_f32_e32 v33, 1.0, v135
	v_exp_f32_e32 v133, v133
	v_mul_f32_e32 v135, 0xbfb8aa3b, v34
	v_exp_f32_e32 v135, v135
	v_rcp_f32_e32 v138, v33
	v_add_f32_e32 v33, 1.0, v133
	v_rcp_f32_e32 v133, v33
	v_add_f32_e32 v33, 1.0, v135
	v_mul_f32_e32 v135, 0xbfb8aa3b, v129
	v_exp_f32_e32 v137, v135
	v_mul_f32_e32 v135, 0xbfb8aa3b, v35
	v_exp_f32_e32 v139, v135
	v_rcp_f32_e32 v135, v33
	v_add_f32_e32 v33, 1.0, v137
	v_rcp_f32_e32 v137, v33
	v_add_f32_e32 v33, 1.0, v139
	v_rcp_f32_e32 v139, v33
	v_mov_b32_e32 v141, v128
	v_mov_b32_e32 v128, v65
	v_mov_b32_e32 v140, v64
	v_pk_mul_f32 v[64:65], v[128:129], v[136:137]
	v_mov_b32_e32 v129, v34
	v_mov_b32_e32 v34, v131
	v_mov_b32_e32 v128, v130
	v_pk_mul_f32 v[34:35], v[34:35], v[138:139]
	v_pk_mul_f32 v[132:133], v[140:141], v[132:133]
	v_pk_mul_f32 v[128:129], v[128:129], v[134:135]
	v_bfe_u32 v33, v35, 16, 1
	v_bfe_u32 v131, v65, 16, 1
	v_bfe_u32 v130, v34, 16, 1
	v_add3_u32 v65, v65, v131, s52
	v_add3_u32 v33, v35, v33, s52
	v_bfe_u32 v35, v132, 16, 1
	v_bfe_u32 v131, v128, 16, 1
	v_bfe_u32 v134, v64, 16, 1
	v_add3_u32 v34, v34, v130, s52
	v_bfe_u32 v130, v133, 16, 1
	v_add3_u32 v128, v128, v131, s52
	v_add3_u32 v35, v132, v35, s52
	v_add3_u32 v64, v64, v134, s52
	v_bfe_u32 v134, v129, 16, 1
	v_add3_u32 v130, v133, v130, s52
	v_lshrrev_b32_e32 v35, 16, v35
	v_lshrrev_b32_e32 v128, 16, v128
	v_add3_u32 v129, v129, v134, s52
	v_lshrrev_b32_e32 v132, 16, v130
	v_and_or_b32 v130, v34, s53, v128
	v_and_or_b32 v128, v64, s53, v35
	v_lshl_add_u64 v[34:35], s[40:41], 0, v[60:61]
	v_lshrrev_b32_e32 v129, 16, v129
	v_lshlrev_b64 v[34:35], 11, v[34:35]
	v_and_or_b32 v131, v33, s53, v129
	v_and_or_b32 v129, v65, s53, v132
	v_lshl_add_u64 v[34:35], v[62:63], 0, v[34:35]
	global_store_dwordx4 v[34:35], v[128:131], off offset:1024
	s_cbranch_scc0 .LBB0_484
